# v55 + grid barriers: s_sleep 1 removed from the 10 polling loops (poll again as soon as the previous poll returns)
# speedup vs baseline: 1.0137x; 1.0035x over previous
.LBB0_171:
	global_load_dword v1, v0, s[74:75] offset:512 sc1
	s_waitcnt vmcnt(0)
	v_cmp_gt_u32_e32 vcc, s92, v1
	s_cbranch_vccnz .LBB0_171

.LBB0_354:
	global_load_dword v1, v0, s[74:75] offset:1024 sc1
	s_waitcnt vmcnt(0)
	v_cmp_gt_u32_e32 vcc, s92, v1
	s_cbranch_vccnz .LBB0_354

.LBB0_573:
	global_load_dword v1, v0, s[74:75] offset:1536 sc1
	s_waitcnt vmcnt(0)
	v_cmp_gt_u32_e32 vcc, s92, v1
	s_cbranch_vccnz .LBB0_573

.LBB0_708:
	global_load_dword v1, v0, s[74:75] offset:2560 sc1
	s_waitcnt vmcnt(0)
	v_cmp_gt_u32_e32 vcc, s92, v1
	s_cbranch_vccnz .LBB0_708

.LBB0_742:
	global_load_dword v1, v0, s[74:75] offset:3072 sc1
	s_waitcnt vmcnt(0)
	v_cmp_gt_u32_e32 vcc, s92, v1
	s_cbranch_vccnz .LBB0_742

.LBB0_820:
	global_load_dword v1, v0, s[74:75] offset:3584 sc1
	s_waitcnt vmcnt(0)
	v_cmp_gt_u32_e32 vcc, s92, v1
	s_cbranch_vccnz .LBB0_820

.LBB0_880:
	global_load_dword v1, v0, s[2:3] sc1
	s_waitcnt vmcnt(0)
	v_cmp_gt_u32_e32 vcc, s92, v1
	s_cbranch_vccnz .LBB0_880
